# p3_tile K-head loop: kh_w loads hoisted, all 8 heads preloaded, loop unrolled with counted waits
# speedup vs baseline: 1.0294x; 1.0012x over previous
.LBB0_482:
	s_or_b64 exec, exec, s[8:9]
	s_waitcnt lgkmcnt(2)
	v_lshlrev_b64 v[0:1], 7, v[2:3]
	v_lshlrev_b32_e32 v6, 5, v27
	v_lshl_add_u64 v[4:5], s[62:63], 0, v[0:1]
	v_and_b32_e32 v24, 0x60, v6
	v_lshl_add_u64 v[0:1], s[2:3], 0, v[0:1]
	v_lshl_add_u64 v[0:1], v[0:1], 0, v[24:25]
	v_lshlrev_b32_e32 v15, 3, v29
	v_readlane_b32 s42, v246, 6
	v_readlane_b32 s43, v246, 7
	v_lshlrev_b32_e32 v202, 5, v29
	v_mov_b32_e32 v203, 0
	global_load_dwordx4 v[50:53], v[0:1], off offset:16
	global_load_dwordx4 v[62:65], v[0:1], off
	v_lshlrev_b64 v[0:1], 12, v[2:3]
	v_lshl_add_u64 v[4:5], v[4:5], 0, v[24:25]
	v_lshl_add_u64 v[38:39], s[6:7], 0, v[0:1]
	v_lshlrev_b32_e32 v24, 1, v15
	v_lshl_add_u64 v[0:1], v[38:39], 0, v[24:25]
	v_lshl_add_u64 v[200:201], v[38:39], 0, v[24:25]
	v_lshl_add_u64 v[202:203], s[42:43], 0, v[202:203]
	global_load_dwordx4 v[20:23], v[0:1], off nt
	global_load_dwordx4 v[16:19], v[0:1], off offset:128 nt
	s_nop 0
	global_load_dwordx4 v[0:3], v[4:5], off
	s_nop 0
	global_load_dwordx4 v[4:7], v[4:5], off offset:16
	global_load_dwordx4 v[212:215], v[202:203], off
	global_load_dwordx4 v[216:219], v[202:203], off offset:16
	global_load_dwordx4 v[220:223], v[202:203], off offset:256
	global_load_dwordx4 v[224:227], v[202:203], off offset:272
	global_load_dwordx4 v[228:231], v[202:203], off offset:528
	global_load_dwordx4 v[232:235], v[202:203], off offset:512
	global_load_dwordx4 v[136:139], v[200:201], off offset:512 nt
	global_load_dwordx4 v[132:135], v[200:201], off offset:640 nt
	global_load_dwordx4 v[144:147], v[200:201], off offset:1024 nt
	global_load_dwordx4 v[140:143], v[200:201], off offset:1152 nt
	global_load_dwordx4 v[160:163], v[200:201], off offset:1536 nt
	global_load_dwordx4 v[156:159], v[200:201], off offset:1664 nt
	global_load_dwordx4 v[168:171], v[200:201], off offset:2048 nt
	global_load_dwordx4 v[164:167], v[200:201], off offset:2176 nt
	global_load_dwordx4 v[176:179], v[200:201], off offset:2560 nt
	global_load_dwordx4 v[172:175], v[200:201], off offset:2688 nt
	global_load_dwordx4 v[184:187], v[200:201], off offset:3072 nt
	global_load_dwordx4 v[180:183], v[200:201], off offset:3200 nt
	global_load_dwordx4 v[192:195], v[200:201], off offset:3584 nt
	global_load_dwordx4 v[188:191], v[200:201], off offset:3712 nt
	s_ashr_i32 s9, s15, 31
	s_waitcnt lgkmcnt(1)
	v_add_f32_e32 v9, v9, v12
	v_cmp_gt_u32_e32 vcc, 4, v29
	s_lshr_b32 s9, s9, 19
	v_fmamk_f32 v9, v9, 0x3b000000, v55
	s_ashr_i32 s8, s20, 31
	s_waitcnt lgkmcnt(0)
	v_add_f32_e32 v60, v13, v14
	v_cndmask_b32_e64 v12, 1.0, -1.0, vcc
	s_add_i32 s9, s15, s9
	v_mul_f32_e32 v13, 0x4b800000, v9
	v_cmp_gt_f32_e32 vcc, s16, v9
	v_lshlrev_b64 v[10:11], 12, v[10:11]
	s_lshr_b32 s8, s8, 25
	s_and_b32 s9, s9, 0xffffe000
	v_cndmask_b32_e32 v9, v9, v13, vcc
	v_or_b32_e32 v10, v10, v8
	s_add_i32 s8, s20, s8
	s_sub_i32 s60, s15, s9
	v_rsq_f32_e32 v9, v9
	v_lshl_add_u64 v[40:41], s[90:91], 0, v[10:11]
	s_ashr_i32 s8, s8, 7
	v_add_u32_e32 v10, s60, v28
	s_lshl_b32 s8, s8, 3
	v_mad_i64_i32 v[10:11], s[22:23], v10, s17, 0
	v_mad_i64_i32 v[10:11], s[22:23], s8, v56, v[10:11]
	v_readlane_b32 s36, v246, 0
	v_mul_f32_e32 v13, 0x45800000, v9
	v_or_b32_e32 v10, v10, v8
	v_lshlrev_b32_e32 v24, 2, v15
	v_readlane_b32 s42, v246, 6
	v_readlane_b32 s43, v246, 7
	v_cndmask_b32_e32 v26, v9, v13, vcc
	v_lshl_add_u64 v[44:45], s[34:35], 0, v[10:11]
	s_mov_b64 s[58:59], 0
	v_lshl_add_u64 v[42:43], s[42:43], 0, v[24:25]
	v_readlane_b32 s37, v246, 1
	v_readlane_b32 s38, v246, 2
	v_readlane_b32 s39, v246, 3
	v_readlane_b32 s40, v246, 4
	v_readlane_b32 s41, v246, 5
	v_readlane_b32 s44, v246, 8
	v_readlane_b32 s45, v246, 9
	v_readlane_b32 s46, v246, 10
	v_readlane_b32 s47, v246, 11
	v_readlane_b32 s48, v246, 12
	v_readlane_b32 s49, v246, 13
	v_readlane_b32 s50, v246, 14
	v_readlane_b32 s51, v246, 15
	s_waitcnt vmcnt(25)
	v_pk_mul_f32 v[48:49], v[12:13], v[50:51] op_sel_hi:[0,1]
	s_waitcnt vmcnt(24)
	v_pk_mul_f32 v[46:47], v[12:13], v[62:63] op_sel_hi:[0,1]
	v_pk_mul_f32 v[50:51], v[12:13], v[64:65] op_sel_hi:[0,1]
	v_pk_mul_f32 v[52:53], v[12:13], v[52:53] op_sel_hi:[0,1]
	s_waitcnt vmcnt(23)
	s_waitcnt vmcnt(22)
	s_waitcnt vmcnt(14)
	v_lshlrev_b32_e32 v94, 16, v16
	v_and_b32_e32 v95, 0xffff0000, v16
	v_lshlrev_b32_e32 v86, 16, v23
	v_and_b32_e32 v87, 0xffff0000, v23
	v_lshlrev_b32_e32 v88, 16, v22
	v_and_b32_e32 v89, 0xffff0000, v22
	v_lshlrev_b32_e32 v22, 16, v21
	v_and_b32_e32 v23, 0xffff0000, v21
	v_lshlrev_b32_e32 v90, 16, v20
	v_and_b32_e32 v91, 0xffff0000, v20
	v_lshlrev_b32_e32 v20, 16, v19
	v_and_b32_e32 v21, 0xffff0000, v19
	v_lshlrev_b32_e32 v92, 16, v18
	v_and_b32_e32 v93, 0xffff0000, v18
	v_lshlrev_b32_e32 v18, 16, v17
	v_and_b32_e32 v19, 0xffff0000, v17
	v_pk_mul_f32 v[100:101], v[94:95], v[94:95]
	v_pk_mul_f32 v[98:99], v[18:19], v[18:19]
	v_pk_fma_f32 v[100:101], v[90:91], v[90:91], v[100:101]
	v_pk_fma_f32 v[98:99], v[22:23], v[22:23], v[98:99]
	v_add_f32_e32 v24, v100, v101
	v_pk_mul_f32 v[96:97], v[92:93], v[92:93]
	v_add_f32_e32 v24, v98, v24
	v_pk_fma_f32 v[96:97], v[88:89], v[88:89], v[96:97]
	v_add_f32_e32 v24, v99, v24
	v_pk_mul_f32 v[16:17], v[20:21], v[20:21]
	v_add_f32_e32 v24, v96, v24
	v_pk_fma_f32 v[16:17], v[86:87], v[86:87], v[16:17]
	v_add_f32_e32 v24, v97, v24
	v_add_f32_e32 v16, v16, v24
	v_add_f32_e32 v16, v17, v16
	ds_bpermute_b32 v17, v57, v16
	s_waitcnt lgkmcnt(0)
	v_add_f32_e32 v16, v16, v17
	ds_bpermute_b32 v17, v58, v16
	s_waitcnt lgkmcnt(0)
	v_add_f32_e32 v16, v16, v17
	ds_bpermute_b32 v17, v59, v16
	s_waitcnt lgkmcnt(0)
	v_add_f32_e32 v16, v16, v17
	v_mul_f32_e32 v16, v26, v16
	v_fma_f32 v16, v26, v16, v60
	v_fmamk_f32 v16, v16, 0x3baaaaab, v55
	v_mul_f32_e32 v17, 0x4b800000, v16
	v_cmp_gt_f32_e32 vcc, s16, v16
	s_nop 1
	v_cndmask_b32_e32 v16, v16, v17, vcc
	v_rsq_f32_e32 v16, v16
	s_nop 0
	v_mul_f32_e32 v17, 0x45800000, v16
	v_cndmask_b32_e32 v24, v16, v17, vcc
	v_mul_f32_e32 v16, v26, v24
	v_pk_mul_f32 v[96:97], v[24:25], v[30:31] op_sel_hi:[0,1]
	v_pk_mul_f32 v[90:91], v[16:17], v[90:91] op_sel_hi:[0,1]
	v_pk_mul_f32 v[88:89], v[16:17], v[88:89] op_sel_hi:[0,1]
	v_pk_mul_f32 v[94:95], v[16:17], v[94:95] op_sel_hi:[0,1]
	v_pk_mul_f32 v[92:93], v[16:17], v[92:93] op_sel_hi:[0,1]
	v_pk_mul_f32 v[22:23], v[16:17], v[22:23] op_sel_hi:[0,1]
	v_pk_mul_f32 v[86:87], v[16:17], v[86:87] op_sel_hi:[0,1]
	v_pk_mul_f32 v[18:19], v[16:17], v[18:19] op_sel_hi:[0,1]
	v_pk_mul_f32 v[16:17], v[16:17], v[20:21] op_sel_hi:[0,1]
	v_pk_mul_f32 v[98:99], v[24:25], v[32:33] op_sel_hi:[0,1]
	v_pk_mul_f32 v[20:21], v[212:213], v[90:91]
	v_pk_mul_f32 v[62:63], v[216:217], v[88:89]
	v_pk_mul_f32 v[66:67], v[220:221], v[94:95]
	v_pk_mul_f32 v[70:71], v[224:225], v[92:93]
	v_pk_mul_f32 v[22:23], v[214:215], v[22:23]
	v_pk_mul_f32 v[74:75], v[232:233], v[96:97]
	v_pk_mul_f32 v[64:65], v[218:219], v[86:87]
	v_pk_mul_f32 v[68:69], v[222:223], v[18:19]
	v_cvt_pk_bf16_f32 v18, v62, v63
	ds_bpermute_b32 v62, v59, v74
	ds_bpermute_b32 v63, v59, v75
	v_pk_mul_f32 v[72:73], v[226:227], v[16:17]
	v_cvt_pk_bf16_f32 v16, v20, v21
	v_cvt_pk_bf16_f32 v17, v22, v23
	v_cvt_pk_bf16_f32 v19, v64, v65
	v_cvt_pk_bf16_f32 v20, v66, v67
	v_cvt_pk_bf16_f32 v21, v68, v69
	v_cvt_pk_bf16_f32 v22, v70, v71
	v_cvt_pk_bf16_f32 v23, v72, v73
	v_pk_mul_f32 v[64:65], v[0:1], v[74:75]
	global_store_dwordx4 v[44:45], v[16:19], off offset:-128
	global_store_dwordx4 v[44:45], v[20:23], off
	v_pk_mul_f32 v[76:77], v[234:235], v[98:99]
	s_waitcnt lgkmcnt(0)
	v_pk_fma_f32 v[16:17], v[46:47], v[62:63], v[64:65]
	v_pk_mul_f32 v[20:21], v[24:25], v[34:35] op_sel_hi:[0,1]
	v_pk_mul_f32 v[20:21], v[228:229], v[20:21]
	v_pk_mul_f32 v[62:63], v[24:25], v[36:37] op_sel_hi:[0,1]
	ds_bpermute_b32 v22, v59, v20
	ds_bpermute_b32 v23, v59, v21
	v_pk_mul_f32 v[62:63], v[230:231], v[62:63]
	ds_bpermute_b32 v64, v59, v62
	ds_bpermute_b32 v65, v59, v63
	ds_bpermute_b32 v18, v59, v76
	ds_bpermute_b32 v19, v59, v77
	s_waitcnt lgkmcnt(4)
	v_pk_mul_f32 v[22:23], v[48:49], v[22:23]
	v_pk_mul_f32 v[66:67], v[2:3], v[76:77]
	v_pk_fma_f32 v[20:21], v[4:5], v[20:21], v[22:23]
	s_waitcnt lgkmcnt(2)
	v_pk_mul_f32 v[22:23], v[52:53], v[64:65]
	s_waitcnt lgkmcnt(0)
	v_pk_fma_f32 v[18:19], v[50:51], v[18:19], v[66:67]
	v_pk_fma_f32 v[22:23], v[6:7], v[62:63], v[22:23]
	v_cvt_pk_bf16_f32 v16, v16, v17
	v_cvt_pk_bf16_f32 v17, v18, v19
	v_cvt_pk_bf16_f32 v18, v20, v21
	v_cvt_pk_bf16_f32 v19, v22, v23
	global_store_dwordx4 v[44:45], v[16:19], off offset:128
	v_lshl_add_u64 v[44:45], v[44:45], 0, s[56:57]
	s_waitcnt vmcnt(15)
	v_mov_b64_e32 v[16:17], v[132:133]
	v_mov_b64_e32 v[18:19], v[134:135]
	v_mov_b64_e32 v[20:21], v[136:137]
	v_mov_b64_e32 v[22:23], v[138:139]
	v_lshlrev_b32_e32 v94, 16, v16
	v_and_b32_e32 v95, 0xffff0000, v16
	v_lshlrev_b32_e32 v86, 16, v23
	v_and_b32_e32 v87, 0xffff0000, v23
	v_lshlrev_b32_e32 v88, 16, v22
	v_and_b32_e32 v89, 0xffff0000, v22
	v_lshlrev_b32_e32 v22, 16, v21
	v_and_b32_e32 v23, 0xffff0000, v21
	v_lshlrev_b32_e32 v90, 16, v20
	v_and_b32_e32 v91, 0xffff0000, v20
	v_lshlrev_b32_e32 v20, 16, v19
	v_and_b32_e32 v21, 0xffff0000, v19
	v_lshlrev_b32_e32 v92, 16, v18
	v_and_b32_e32 v93, 0xffff0000, v18
	v_lshlrev_b32_e32 v18, 16, v17
	v_and_b32_e32 v19, 0xffff0000, v17
	v_pk_mul_f32 v[100:101], v[94:95], v[94:95]
	v_pk_mul_f32 v[98:99], v[18:19], v[18:19]
	v_pk_fma_f32 v[100:101], v[90:91], v[90:91], v[100:101]
	v_pk_fma_f32 v[98:99], v[22:23], v[22:23], v[98:99]
	v_add_f32_e32 v24, v100, v101
	v_pk_mul_f32 v[96:97], v[92:93], v[92:93]
	v_add_f32_e32 v24, v98, v24
	v_pk_fma_f32 v[96:97], v[88:89], v[88:89], v[96:97]
	v_add_f32_e32 v24, v99, v24
	v_pk_mul_f32 v[16:17], v[20:21], v[20:21]
	v_add_f32_e32 v24, v96, v24
	v_pk_fma_f32 v[16:17], v[86:87], v[86:87], v[16:17]
	v_add_f32_e32 v24, v97, v24
	v_add_f32_e32 v16, v16, v24
	v_add_f32_e32 v16, v17, v16
	ds_bpermute_b32 v17, v57, v16
	s_waitcnt lgkmcnt(0)
	v_add_f32_e32 v16, v16, v17
	ds_bpermute_b32 v17, v58, v16
	s_waitcnt lgkmcnt(0)
	v_add_f32_e32 v16, v16, v17
	ds_bpermute_b32 v17, v59, v16
	s_waitcnt lgkmcnt(0)
	v_add_f32_e32 v16, v16, v17
	v_mul_f32_e32 v16, v26, v16
	v_fma_f32 v16, v26, v16, v60
	v_fmamk_f32 v16, v16, 0x3baaaaab, v55
	v_mul_f32_e32 v17, 0x4b800000, v16
	v_cmp_gt_f32_e32 vcc, s16, v16
	s_nop 1
	v_cndmask_b32_e32 v16, v16, v17, vcc
	v_rsq_f32_e32 v16, v16
	s_nop 0
	v_mul_f32_e32 v17, 0x45800000, v16
	v_cndmask_b32_e32 v24, v16, v17, vcc
	v_mul_f32_e32 v16, v26, v24
	v_pk_mul_f32 v[96:97], v[24:25], v[30:31] op_sel_hi:[0,1]
	v_pk_mul_f32 v[90:91], v[16:17], v[90:91] op_sel_hi:[0,1]
	v_pk_mul_f32 v[88:89], v[16:17], v[88:89] op_sel_hi:[0,1]
	v_pk_mul_f32 v[94:95], v[16:17], v[94:95] op_sel_hi:[0,1]
	v_pk_mul_f32 v[92:93], v[16:17], v[92:93] op_sel_hi:[0,1]
	v_pk_mul_f32 v[22:23], v[16:17], v[22:23] op_sel_hi:[0,1]
	v_pk_mul_f32 v[86:87], v[16:17], v[86:87] op_sel_hi:[0,1]
	v_pk_mul_f32 v[18:19], v[16:17], v[18:19] op_sel_hi:[0,1]
	v_pk_mul_f32 v[16:17], v[16:17], v[20:21] op_sel_hi:[0,1]
	v_pk_mul_f32 v[98:99], v[24:25], v[32:33] op_sel_hi:[0,1]
	v_pk_mul_f32 v[20:21], v[212:213], v[90:91]
	v_pk_mul_f32 v[62:63], v[216:217], v[88:89]
	v_pk_mul_f32 v[66:67], v[220:221], v[94:95]
	v_pk_mul_f32 v[70:71], v[224:225], v[92:93]
	v_pk_mul_f32 v[22:23], v[214:215], v[22:23]
	v_pk_mul_f32 v[74:75], v[232:233], v[96:97]
	v_pk_mul_f32 v[64:65], v[218:219], v[86:87]
	v_pk_mul_f32 v[68:69], v[222:223], v[18:19]
	v_cvt_pk_bf16_f32 v18, v62, v63
	ds_bpermute_b32 v62, v59, v74
	ds_bpermute_b32 v63, v59, v75
	v_pk_mul_f32 v[72:73], v[226:227], v[16:17]
	v_cvt_pk_bf16_f32 v16, v20, v21
	v_cvt_pk_bf16_f32 v17, v22, v23
	v_cvt_pk_bf16_f32 v19, v64, v65
	v_cvt_pk_bf16_f32 v20, v66, v67
	v_cvt_pk_bf16_f32 v21, v68, v69
	v_cvt_pk_bf16_f32 v22, v70, v71
	v_cvt_pk_bf16_f32 v23, v72, v73
	v_pk_mul_f32 v[64:65], v[0:1], v[74:75]
	global_store_dwordx4 v[44:45], v[16:19], off offset:-128
	global_store_dwordx4 v[44:45], v[20:23], off
	v_pk_mul_f32 v[76:77], v[234:235], v[98:99]
	s_waitcnt lgkmcnt(0)
	v_pk_fma_f32 v[16:17], v[46:47], v[62:63], v[64:65]
	v_pk_mul_f32 v[20:21], v[24:25], v[34:35] op_sel_hi:[0,1]
	v_pk_mul_f32 v[20:21], v[228:229], v[20:21]
	v_pk_mul_f32 v[62:63], v[24:25], v[36:37] op_sel_hi:[0,1]
	ds_bpermute_b32 v22, v59, v20
	ds_bpermute_b32 v23, v59, v21
	v_pk_mul_f32 v[62:63], v[230:231], v[62:63]
	ds_bpermute_b32 v64, v59, v62
	ds_bpermute_b32 v65, v59, v63
	ds_bpermute_b32 v18, v59, v76
	ds_bpermute_b32 v19, v59, v77
	s_waitcnt lgkmcnt(4)
	v_pk_mul_f32 v[22:23], v[48:49], v[22:23]
	v_pk_mul_f32 v[66:67], v[2:3], v[76:77]
	v_pk_fma_f32 v[20:21], v[4:5], v[20:21], v[22:23]
	s_waitcnt lgkmcnt(2)
	v_pk_mul_f32 v[22:23], v[52:53], v[64:65]
	s_waitcnt lgkmcnt(0)
	v_pk_fma_f32 v[18:19], v[50:51], v[18:19], v[66:67]
	v_pk_fma_f32 v[22:23], v[6:7], v[62:63], v[22:23]
	v_cvt_pk_bf16_f32 v16, v16, v17
	v_cvt_pk_bf16_f32 v17, v18, v19
	v_cvt_pk_bf16_f32 v18, v20, v21
	v_cvt_pk_bf16_f32 v19, v22, v23
	global_store_dwordx4 v[44:45], v[16:19], off offset:128
	v_lshl_add_u64 v[44:45], v[44:45], 0, s[56:57]
	s_waitcnt vmcnt(16)
	v_mov_b64_e32 v[16:17], v[140:141]
	v_mov_b64_e32 v[18:19], v[142:143]
	v_mov_b64_e32 v[20:21], v[144:145]
	v_mov_b64_e32 v[22:23], v[146:147]
	v_lshlrev_b32_e32 v94, 16, v16
	v_and_b32_e32 v95, 0xffff0000, v16
	v_lshlrev_b32_e32 v86, 16, v23
	v_and_b32_e32 v87, 0xffff0000, v23
	v_lshlrev_b32_e32 v88, 16, v22
	v_and_b32_e32 v89, 0xffff0000, v22
	v_lshlrev_b32_e32 v22, 16, v21
	v_and_b32_e32 v23, 0xffff0000, v21
	v_lshlrev_b32_e32 v90, 16, v20
	v_and_b32_e32 v91, 0xffff0000, v20
	v_lshlrev_b32_e32 v20, 16, v19
	v_and_b32_e32 v21, 0xffff0000, v19
	v_lshlrev_b32_e32 v92, 16, v18
	v_and_b32_e32 v93, 0xffff0000, v18
	v_lshlrev_b32_e32 v18, 16, v17
	v_and_b32_e32 v19, 0xffff0000, v17
	v_pk_mul_f32 v[100:101], v[94:95], v[94:95]
	v_pk_mul_f32 v[98:99], v[18:19], v[18:19]
	v_pk_fma_f32 v[100:101], v[90:91], v[90:91], v[100:101]
	v_pk_fma_f32 v[98:99], v[22:23], v[22:23], v[98:99]
	v_add_f32_e32 v24, v100, v101
	v_pk_mul_f32 v[96:97], v[92:93], v[92:93]
	v_add_f32_e32 v24, v98, v24
	v_pk_fma_f32 v[96:97], v[88:89], v[88:89], v[96:97]
	v_add_f32_e32 v24, v99, v24
	v_pk_mul_f32 v[16:17], v[20:21], v[20:21]
	v_add_f32_e32 v24, v96, v24
	v_pk_fma_f32 v[16:17], v[86:87], v[86:87], v[16:17]
	v_add_f32_e32 v24, v97, v24
	v_add_f32_e32 v16, v16, v24
	v_add_f32_e32 v16, v17, v16
	ds_bpermute_b32 v17, v57, v16
	s_waitcnt lgkmcnt(0)
	v_add_f32_e32 v16, v16, v17
	ds_bpermute_b32 v17, v58, v16
	s_waitcnt lgkmcnt(0)
	v_add_f32_e32 v16, v16, v17
	ds_bpermute_b32 v17, v59, v16
	s_waitcnt lgkmcnt(0)
	v_add_f32_e32 v16, v16, v17
	v_mul_f32_e32 v16, v26, v16
	v_fma_f32 v16, v26, v16, v60
	v_fmamk_f32 v16, v16, 0x3baaaaab, v55
	v_mul_f32_e32 v17, 0x4b800000, v16
	v_cmp_gt_f32_e32 vcc, s16, v16
	s_nop 1
	v_cndmask_b32_e32 v16, v16, v17, vcc
	v_rsq_f32_e32 v16, v16
	s_nop 0
	v_mul_f32_e32 v17, 0x45800000, v16
	v_cndmask_b32_e32 v24, v16, v17, vcc
	v_mul_f32_e32 v16, v26, v24
	v_pk_mul_f32 v[96:97], v[24:25], v[30:31] op_sel_hi:[0,1]
	v_pk_mul_f32 v[90:91], v[16:17], v[90:91] op_sel_hi:[0,1]
	v_pk_mul_f32 v[88:89], v[16:17], v[88:89] op_sel_hi:[0,1]
	v_pk_mul_f32 v[94:95], v[16:17], v[94:95] op_sel_hi:[0,1]
	v_pk_mul_f32 v[92:93], v[16:17], v[92:93] op_sel_hi:[0,1]
	v_pk_mul_f32 v[22:23], v[16:17], v[22:23] op_sel_hi:[0,1]
	v_pk_mul_f32 v[86:87], v[16:17], v[86:87] op_sel_hi:[0,1]
	v_pk_mul_f32 v[18:19], v[16:17], v[18:19] op_sel_hi:[0,1]
	v_pk_mul_f32 v[16:17], v[16:17], v[20:21] op_sel_hi:[0,1]
	v_pk_mul_f32 v[98:99], v[24:25], v[32:33] op_sel_hi:[0,1]
	v_pk_mul_f32 v[20:21], v[212:213], v[90:91]
	v_pk_mul_f32 v[62:63], v[216:217], v[88:89]
	v_pk_mul_f32 v[66:67], v[220:221], v[94:95]
	v_pk_mul_f32 v[70:71], v[224:225], v[92:93]
	v_pk_mul_f32 v[22:23], v[214:215], v[22:23]
	v_pk_mul_f32 v[74:75], v[232:233], v[96:97]
	v_pk_mul_f32 v[64:65], v[218:219], v[86:87]
	v_pk_mul_f32 v[68:69], v[222:223], v[18:19]
	v_cvt_pk_bf16_f32 v18, v62, v63
	ds_bpermute_b32 v62, v59, v74
	ds_bpermute_b32 v63, v59, v75
	v_pk_mul_f32 v[72:73], v[226:227], v[16:17]
	v_cvt_pk_bf16_f32 v16, v20, v21
	v_cvt_pk_bf16_f32 v17, v22, v23
	v_cvt_pk_bf16_f32 v19, v64, v65
	v_cvt_pk_bf16_f32 v20, v66, v67
	v_cvt_pk_bf16_f32 v21, v68, v69
	v_cvt_pk_bf16_f32 v22, v70, v71
	v_cvt_pk_bf16_f32 v23, v72, v73
	v_pk_mul_f32 v[64:65], v[0:1], v[74:75]
	global_store_dwordx4 v[44:45], v[16:19], off offset:-128
	global_store_dwordx4 v[44:45], v[20:23], off
	v_pk_mul_f32 v[76:77], v[234:235], v[98:99]
	s_waitcnt lgkmcnt(0)
	v_pk_fma_f32 v[16:17], v[46:47], v[62:63], v[64:65]
	v_pk_mul_f32 v[20:21], v[24:25], v[34:35] op_sel_hi:[0,1]
	v_pk_mul_f32 v[20:21], v[228:229], v[20:21]
	v_pk_mul_f32 v[62:63], v[24:25], v[36:37] op_sel_hi:[0,1]
	ds_bpermute_b32 v22, v59, v20
	ds_bpermute_b32 v23, v59, v21
	v_pk_mul_f32 v[62:63], v[230:231], v[62:63]
	ds_bpermute_b32 v64, v59, v62
	ds_bpermute_b32 v65, v59, v63
	ds_bpermute_b32 v18, v59, v76
	ds_bpermute_b32 v19, v59, v77
	s_waitcnt lgkmcnt(4)
	v_pk_mul_f32 v[22:23], v[48:49], v[22:23]
	v_pk_mul_f32 v[66:67], v[2:3], v[76:77]
	v_pk_fma_f32 v[20:21], v[4:5], v[20:21], v[22:23]
	s_waitcnt lgkmcnt(2)
	v_pk_mul_f32 v[22:23], v[52:53], v[64:65]
	s_waitcnt lgkmcnt(0)
	v_pk_fma_f32 v[18:19], v[50:51], v[18:19], v[66:67]
	v_pk_fma_f32 v[22:23], v[6:7], v[62:63], v[22:23]
	v_cvt_pk_bf16_f32 v16, v16, v17
	v_cvt_pk_bf16_f32 v17, v18, v19
	v_cvt_pk_bf16_f32 v18, v20, v21
	v_cvt_pk_bf16_f32 v19, v22, v23
	global_store_dwordx4 v[44:45], v[16:19], off offset:128
	v_lshl_add_u64 v[44:45], v[44:45], 0, s[56:57]
	s_waitcnt vmcnt(17)
	v_mov_b64_e32 v[16:17], v[156:157]
	v_mov_b64_e32 v[18:19], v[158:159]
	v_mov_b64_e32 v[20:21], v[160:161]
	v_mov_b64_e32 v[22:23], v[162:163]
	v_lshlrev_b32_e32 v94, 16, v16
	v_and_b32_e32 v95, 0xffff0000, v16
	v_lshlrev_b32_e32 v86, 16, v23
	v_and_b32_e32 v87, 0xffff0000, v23
	v_lshlrev_b32_e32 v88, 16, v22
	v_and_b32_e32 v89, 0xffff0000, v22
	v_lshlrev_b32_e32 v22, 16, v21
	v_and_b32_e32 v23, 0xffff0000, v21
	v_lshlrev_b32_e32 v90, 16, v20
	v_and_b32_e32 v91, 0xffff0000, v20
	v_lshlrev_b32_e32 v20, 16, v19
	v_and_b32_e32 v21, 0xffff0000, v19
	v_lshlrev_b32_e32 v92, 16, v18
	v_and_b32_e32 v93, 0xffff0000, v18
	v_lshlrev_b32_e32 v18, 16, v17
	v_and_b32_e32 v19, 0xffff0000, v17
	v_pk_mul_f32 v[100:101], v[94:95], v[94:95]
	v_pk_mul_f32 v[98:99], v[18:19], v[18:19]
	v_pk_fma_f32 v[100:101], v[90:91], v[90:91], v[100:101]
	v_pk_fma_f32 v[98:99], v[22:23], v[22:23], v[98:99]
	v_add_f32_e32 v24, v100, v101
	v_pk_mul_f32 v[96:97], v[92:93], v[92:93]
	v_add_f32_e32 v24, v98, v24
	v_pk_fma_f32 v[96:97], v[88:89], v[88:89], v[96:97]
	v_add_f32_e32 v24, v99, v24
	v_pk_mul_f32 v[16:17], v[20:21], v[20:21]
	v_add_f32_e32 v24, v96, v24
	v_pk_fma_f32 v[16:17], v[86:87], v[86:87], v[16:17]
	v_add_f32_e32 v24, v97, v24
	v_add_f32_e32 v16, v16, v24
	v_add_f32_e32 v16, v17, v16
	ds_bpermute_b32 v17, v57, v16
	s_waitcnt lgkmcnt(0)
	v_add_f32_e32 v16, v16, v17
	ds_bpermute_b32 v17, v58, v16
	s_waitcnt lgkmcnt(0)
	v_add_f32_e32 v16, v16, v17
	ds_bpermute_b32 v17, v59, v16
	s_waitcnt lgkmcnt(0)
	v_add_f32_e32 v16, v16, v17
	v_mul_f32_e32 v16, v26, v16
	v_fma_f32 v16, v26, v16, v60
	v_fmamk_f32 v16, v16, 0x3baaaaab, v55
	v_mul_f32_e32 v17, 0x4b800000, v16
	v_cmp_gt_f32_e32 vcc, s16, v16
	s_nop 1
	v_cndmask_b32_e32 v16, v16, v17, vcc
	v_rsq_f32_e32 v16, v16
	s_nop 0
	v_mul_f32_e32 v17, 0x45800000, v16
	v_cndmask_b32_e32 v24, v16, v17, vcc
	v_mul_f32_e32 v16, v26, v24
	v_pk_mul_f32 v[96:97], v[24:25], v[30:31] op_sel_hi:[0,1]
	v_pk_mul_f32 v[90:91], v[16:17], v[90:91] op_sel_hi:[0,1]
	v_pk_mul_f32 v[88:89], v[16:17], v[88:89] op_sel_hi:[0,1]
	v_pk_mul_f32 v[94:95], v[16:17], v[94:95] op_sel_hi:[0,1]
	v_pk_mul_f32 v[92:93], v[16:17], v[92:93] op_sel_hi:[0,1]
	v_pk_mul_f32 v[22:23], v[16:17], v[22:23] op_sel_hi:[0,1]
	v_pk_mul_f32 v[86:87], v[16:17], v[86:87] op_sel_hi:[0,1]
	v_pk_mul_f32 v[18:19], v[16:17], v[18:19] op_sel_hi:[0,1]
	v_pk_mul_f32 v[16:17], v[16:17], v[20:21] op_sel_hi:[0,1]
	v_pk_mul_f32 v[98:99], v[24:25], v[32:33] op_sel_hi:[0,1]
	v_pk_mul_f32 v[20:21], v[212:213], v[90:91]
	v_pk_mul_f32 v[62:63], v[216:217], v[88:89]
	v_pk_mul_f32 v[66:67], v[220:221], v[94:95]
	v_pk_mul_f32 v[70:71], v[224:225], v[92:93]
	v_pk_mul_f32 v[22:23], v[214:215], v[22:23]
	v_pk_mul_f32 v[74:75], v[232:233], v[96:97]
	v_pk_mul_f32 v[64:65], v[218:219], v[86:87]
	v_pk_mul_f32 v[68:69], v[222:223], v[18:19]
	v_cvt_pk_bf16_f32 v18, v62, v63
	ds_bpermute_b32 v62, v59, v74
	ds_bpermute_b32 v63, v59, v75
	v_pk_mul_f32 v[72:73], v[226:227], v[16:17]
	v_cvt_pk_bf16_f32 v16, v20, v21
	v_cvt_pk_bf16_f32 v17, v22, v23
	v_cvt_pk_bf16_f32 v19, v64, v65
	v_cvt_pk_bf16_f32 v20, v66, v67
	v_cvt_pk_bf16_f32 v21, v68, v69
	v_cvt_pk_bf16_f32 v22, v70, v71
	v_cvt_pk_bf16_f32 v23, v72, v73
	v_pk_mul_f32 v[64:65], v[0:1], v[74:75]
	global_store_dwordx4 v[44:45], v[16:19], off offset:-128
	global_store_dwordx4 v[44:45], v[20:23], off
	v_pk_mul_f32 v[76:77], v[234:235], v[98:99]
	s_waitcnt lgkmcnt(0)
	v_pk_fma_f32 v[16:17], v[46:47], v[62:63], v[64:65]
	v_pk_mul_f32 v[20:21], v[24:25], v[34:35] op_sel_hi:[0,1]
	v_pk_mul_f32 v[20:21], v[228:229], v[20:21]
	v_pk_mul_f32 v[62:63], v[24:25], v[36:37] op_sel_hi:[0,1]
	ds_bpermute_b32 v22, v59, v20
	ds_bpermute_b32 v23, v59, v21
	v_pk_mul_f32 v[62:63], v[230:231], v[62:63]
	ds_bpermute_b32 v64, v59, v62
	ds_bpermute_b32 v65, v59, v63
	ds_bpermute_b32 v18, v59, v76
	ds_bpermute_b32 v19, v59, v77
	s_waitcnt lgkmcnt(4)
	v_pk_mul_f32 v[22:23], v[48:49], v[22:23]
	v_pk_mul_f32 v[66:67], v[2:3], v[76:77]
	v_pk_fma_f32 v[20:21], v[4:5], v[20:21], v[22:23]
	s_waitcnt lgkmcnt(2)
	v_pk_mul_f32 v[22:23], v[52:53], v[64:65]
	s_waitcnt lgkmcnt(0)
	v_pk_fma_f32 v[18:19], v[50:51], v[18:19], v[66:67]
	v_pk_fma_f32 v[22:23], v[6:7], v[62:63], v[22:23]
	v_cvt_pk_bf16_f32 v16, v16, v17
	v_cvt_pk_bf16_f32 v17, v18, v19
	v_cvt_pk_bf16_f32 v18, v20, v21
	v_cvt_pk_bf16_f32 v19, v22, v23
	global_store_dwordx4 v[44:45], v[16:19], off offset:128
	v_lshl_add_u64 v[44:45], v[44:45], 0, s[56:57]
	s_waitcnt vmcnt(18)
	v_mov_b64_e32 v[16:17], v[164:165]
	v_mov_b64_e32 v[18:19], v[166:167]
	v_mov_b64_e32 v[20:21], v[168:169]
	v_mov_b64_e32 v[22:23], v[170:171]
	v_lshlrev_b32_e32 v94, 16, v16
	v_and_b32_e32 v95, 0xffff0000, v16
	v_lshlrev_b32_e32 v86, 16, v23
	v_and_b32_e32 v87, 0xffff0000, v23
	v_lshlrev_b32_e32 v88, 16, v22
	v_and_b32_e32 v89, 0xffff0000, v22
	v_lshlrev_b32_e32 v22, 16, v21
	v_and_b32_e32 v23, 0xffff0000, v21
	v_lshlrev_b32_e32 v90, 16, v20
	v_and_b32_e32 v91, 0xffff0000, v20
	v_lshlrev_b32_e32 v20, 16, v19
	v_and_b32_e32 v21, 0xffff0000, v19
	v_lshlrev_b32_e32 v92, 16, v18
	v_and_b32_e32 v93, 0xffff0000, v18
	v_lshlrev_b32_e32 v18, 16, v17
	v_and_b32_e32 v19, 0xffff0000, v17
	v_pk_mul_f32 v[100:101], v[94:95], v[94:95]
	v_pk_mul_f32 v[98:99], v[18:19], v[18:19]
	v_pk_fma_f32 v[100:101], v[90:91], v[90:91], v[100:101]
	v_pk_fma_f32 v[98:99], v[22:23], v[22:23], v[98:99]
	v_add_f32_e32 v24, v100, v101
	v_pk_mul_f32 v[96:97], v[92:93], v[92:93]
	v_add_f32_e32 v24, v98, v24
	v_pk_fma_f32 v[96:97], v[88:89], v[88:89], v[96:97]
	v_add_f32_e32 v24, v99, v24
	v_pk_mul_f32 v[16:17], v[20:21], v[20:21]
	v_add_f32_e32 v24, v96, v24
	v_pk_fma_f32 v[16:17], v[86:87], v[86:87], v[16:17]
	v_add_f32_e32 v24, v97, v24
	v_add_f32_e32 v16, v16, v24
	v_add_f32_e32 v16, v17, v16
	ds_bpermute_b32 v17, v57, v16
	s_waitcnt lgkmcnt(0)
	v_add_f32_e32 v16, v16, v17
	ds_bpermute_b32 v17, v58, v16
	s_waitcnt lgkmcnt(0)
	v_add_f32_e32 v16, v16, v17
	ds_bpermute_b32 v17, v59, v16
	s_waitcnt lgkmcnt(0)
	v_add_f32_e32 v16, v16, v17
	v_mul_f32_e32 v16, v26, v16
	v_fma_f32 v16, v26, v16, v60
	v_fmamk_f32 v16, v16, 0x3baaaaab, v55
	v_mul_f32_e32 v17, 0x4b800000, v16
	v_cmp_gt_f32_e32 vcc, s16, v16
	s_nop 1
	v_cndmask_b32_e32 v16, v16, v17, vcc
	v_rsq_f32_e32 v16, v16
	s_nop 0
	v_mul_f32_e32 v17, 0x45800000, v16
	v_cndmask_b32_e32 v24, v16, v17, vcc
	v_mul_f32_e32 v16, v26, v24
	v_pk_mul_f32 v[96:97], v[24:25], v[30:31] op_sel_hi:[0,1]
	v_pk_mul_f32 v[90:91], v[16:17], v[90:91] op_sel_hi:[0,1]
	v_pk_mul_f32 v[88:89], v[16:17], v[88:89] op_sel_hi:[0,1]
	v_pk_mul_f32 v[94:95], v[16:17], v[94:95] op_sel_hi:[0,1]
	v_pk_mul_f32 v[92:93], v[16:17], v[92:93] op_sel_hi:[0,1]
	v_pk_mul_f32 v[22:23], v[16:17], v[22:23] op_sel_hi:[0,1]
	v_pk_mul_f32 v[86:87], v[16:17], v[86:87] op_sel_hi:[0,1]
	v_pk_mul_f32 v[18:19], v[16:17], v[18:19] op_sel_hi:[0,1]
	v_pk_mul_f32 v[16:17], v[16:17], v[20:21] op_sel_hi:[0,1]
	v_pk_mul_f32 v[98:99], v[24:25], v[32:33] op_sel_hi:[0,1]
	v_pk_mul_f32 v[20:21], v[212:213], v[90:91]
	v_pk_mul_f32 v[62:63], v[216:217], v[88:89]
	v_pk_mul_f32 v[66:67], v[220:221], v[94:95]
	v_pk_mul_f32 v[70:71], v[224:225], v[92:93]
	v_pk_mul_f32 v[22:23], v[214:215], v[22:23]
	v_pk_mul_f32 v[74:75], v[232:233], v[96:97]
	v_pk_mul_f32 v[64:65], v[218:219], v[86:87]
	v_pk_mul_f32 v[68:69], v[222:223], v[18:19]
	v_cvt_pk_bf16_f32 v18, v62, v63
	ds_bpermute_b32 v62, v59, v74
	ds_bpermute_b32 v63, v59, v75
	v_pk_mul_f32 v[72:73], v[226:227], v[16:17]
	v_cvt_pk_bf16_f32 v16, v20, v21
	v_cvt_pk_bf16_f32 v17, v22, v23
	v_cvt_pk_bf16_f32 v19, v64, v65
	v_cvt_pk_bf16_f32 v20, v66, v67
	v_cvt_pk_bf16_f32 v21, v68, v69
	v_cvt_pk_bf16_f32 v22, v70, v71
	v_cvt_pk_bf16_f32 v23, v72, v73
	v_pk_mul_f32 v[64:65], v[0:1], v[74:75]
	global_store_dwordx4 v[44:45], v[16:19], off offset:-128
	global_store_dwordx4 v[44:45], v[20:23], off
	v_pk_mul_f32 v[76:77], v[234:235], v[98:99]
	s_waitcnt lgkmcnt(0)
	v_pk_fma_f32 v[16:17], v[46:47], v[62:63], v[64:65]
	v_pk_mul_f32 v[20:21], v[24:25], v[34:35] op_sel_hi:[0,1]
	v_pk_mul_f32 v[20:21], v[228:229], v[20:21]
	v_pk_mul_f32 v[62:63], v[24:25], v[36:37] op_sel_hi:[0,1]
	ds_bpermute_b32 v22, v59, v20
	ds_bpermute_b32 v23, v59, v21
	v_pk_mul_f32 v[62:63], v[230:231], v[62:63]
	ds_bpermute_b32 v64, v59, v62
	ds_bpermute_b32 v65, v59, v63
	ds_bpermute_b32 v18, v59, v76
	ds_bpermute_b32 v19, v59, v77
	s_waitcnt lgkmcnt(4)
	v_pk_mul_f32 v[22:23], v[48:49], v[22:23]
	v_pk_mul_f32 v[66:67], v[2:3], v[76:77]
	v_pk_fma_f32 v[20:21], v[4:5], v[20:21], v[22:23]
	s_waitcnt lgkmcnt(2)
	v_pk_mul_f32 v[22:23], v[52:53], v[64:65]
	s_waitcnt lgkmcnt(0)
	v_pk_fma_f32 v[18:19], v[50:51], v[18:19], v[66:67]
	v_pk_fma_f32 v[22:23], v[6:7], v[62:63], v[22:23]
	v_cvt_pk_bf16_f32 v16, v16, v17
	v_cvt_pk_bf16_f32 v17, v18, v19
	v_cvt_pk_bf16_f32 v18, v20, v21
	v_cvt_pk_bf16_f32 v19, v22, v23
	global_store_dwordx4 v[44:45], v[16:19], off offset:128
	v_lshl_add_u64 v[44:45], v[44:45], 0, s[56:57]
	s_waitcnt vmcnt(19)
	v_mov_b64_e32 v[16:17], v[172:173]
	v_mov_b64_e32 v[18:19], v[174:175]
	v_mov_b64_e32 v[20:21], v[176:177]
	v_mov_b64_e32 v[22:23], v[178:179]
	v_lshlrev_b32_e32 v94, 16, v16
	v_and_b32_e32 v95, 0xffff0000, v16
	v_lshlrev_b32_e32 v86, 16, v23
	v_and_b32_e32 v87, 0xffff0000, v23
	v_lshlrev_b32_e32 v88, 16, v22
	v_and_b32_e32 v89, 0xffff0000, v22
	v_lshlrev_b32_e32 v22, 16, v21
	v_and_b32_e32 v23, 0xffff0000, v21
	v_lshlrev_b32_e32 v90, 16, v20
	v_and_b32_e32 v91, 0xffff0000, v20
	v_lshlrev_b32_e32 v20, 16, v19
	v_and_b32_e32 v21, 0xffff0000, v19
	v_lshlrev_b32_e32 v92, 16, v18
	v_and_b32_e32 v93, 0xffff0000, v18
	v_lshlrev_b32_e32 v18, 16, v17
	v_and_b32_e32 v19, 0xffff0000, v17
	v_pk_mul_f32 v[100:101], v[94:95], v[94:95]
	v_pk_mul_f32 v[98:99], v[18:19], v[18:19]
	v_pk_fma_f32 v[100:101], v[90:91], v[90:91], v[100:101]
	v_pk_fma_f32 v[98:99], v[22:23], v[22:23], v[98:99]
	v_add_f32_e32 v24, v100, v101
	v_pk_mul_f32 v[96:97], v[92:93], v[92:93]
	v_add_f32_e32 v24, v98, v24
	v_pk_fma_f32 v[96:97], v[88:89], v[88:89], v[96:97]
	v_add_f32_e32 v24, v99, v24
	v_pk_mul_f32 v[16:17], v[20:21], v[20:21]
	v_add_f32_e32 v24, v96, v24
	v_pk_fma_f32 v[16:17], v[86:87], v[86:87], v[16:17]
	v_add_f32_e32 v24, v97, v24
	v_add_f32_e32 v16, v16, v24
	v_add_f32_e32 v16, v17, v16
	ds_bpermute_b32 v17, v57, v16
	s_waitcnt lgkmcnt(0)
	v_add_f32_e32 v16, v16, v17
	ds_bpermute_b32 v17, v58, v16
	s_waitcnt lgkmcnt(0)
	v_add_f32_e32 v16, v16, v17
	ds_bpermute_b32 v17, v59, v16
	s_waitcnt lgkmcnt(0)
	v_add_f32_e32 v16, v16, v17
	v_mul_f32_e32 v16, v26, v16
	v_fma_f32 v16, v26, v16, v60
	v_fmamk_f32 v16, v16, 0x3baaaaab, v55
	v_mul_f32_e32 v17, 0x4b800000, v16
	v_cmp_gt_f32_e32 vcc, s16, v16
	s_nop 1
	v_cndmask_b32_e32 v16, v16, v17, vcc
	v_rsq_f32_e32 v16, v16
	s_nop 0
	v_mul_f32_e32 v17, 0x45800000, v16
	v_cndmask_b32_e32 v24, v16, v17, vcc
	v_mul_f32_e32 v16, v26, v24
	v_pk_mul_f32 v[96:97], v[24:25], v[30:31] op_sel_hi:[0,1]
	v_pk_mul_f32 v[90:91], v[16:17], v[90:91] op_sel_hi:[0,1]
	v_pk_mul_f32 v[88:89], v[16:17], v[88:89] op_sel_hi:[0,1]
	v_pk_mul_f32 v[94:95], v[16:17], v[94:95] op_sel_hi:[0,1]
	v_pk_mul_f32 v[92:93], v[16:17], v[92:93] op_sel_hi:[0,1]
	v_pk_mul_f32 v[22:23], v[16:17], v[22:23] op_sel_hi:[0,1]
	v_pk_mul_f32 v[86:87], v[16:17], v[86:87] op_sel_hi:[0,1]
	v_pk_mul_f32 v[18:19], v[16:17], v[18:19] op_sel_hi:[0,1]
	v_pk_mul_f32 v[16:17], v[16:17], v[20:21] op_sel_hi:[0,1]
	v_pk_mul_f32 v[98:99], v[24:25], v[32:33] op_sel_hi:[0,1]
	v_pk_mul_f32 v[20:21], v[212:213], v[90:91]
	v_pk_mul_f32 v[62:63], v[216:217], v[88:89]
	v_pk_mul_f32 v[66:67], v[220:221], v[94:95]
	v_pk_mul_f32 v[70:71], v[224:225], v[92:93]
	v_pk_mul_f32 v[22:23], v[214:215], v[22:23]
	v_pk_mul_f32 v[74:75], v[232:233], v[96:97]
	v_pk_mul_f32 v[64:65], v[218:219], v[86:87]
	v_pk_mul_f32 v[68:69], v[222:223], v[18:19]
	v_cvt_pk_bf16_f32 v18, v62, v63
	ds_bpermute_b32 v62, v59, v74
	ds_bpermute_b32 v63, v59, v75
	v_pk_mul_f32 v[72:73], v[226:227], v[16:17]
	v_cvt_pk_bf16_f32 v16, v20, v21
	v_cvt_pk_bf16_f32 v17, v22, v23
	v_cvt_pk_bf16_f32 v19, v64, v65
	v_cvt_pk_bf16_f32 v20, v66, v67
	v_cvt_pk_bf16_f32 v21, v68, v69
	v_cvt_pk_bf16_f32 v22, v70, v71
	v_cvt_pk_bf16_f32 v23, v72, v73
	v_pk_mul_f32 v[64:65], v[0:1], v[74:75]
	global_store_dwordx4 v[44:45], v[16:19], off offset:-128
	global_store_dwordx4 v[44:45], v[20:23], off
	v_pk_mul_f32 v[76:77], v[234:235], v[98:99]
	s_waitcnt lgkmcnt(0)
	v_pk_fma_f32 v[16:17], v[46:47], v[62:63], v[64:65]
	v_pk_mul_f32 v[20:21], v[24:25], v[34:35] op_sel_hi:[0,1]
	v_pk_mul_f32 v[20:21], v[228:229], v[20:21]
	v_pk_mul_f32 v[62:63], v[24:25], v[36:37] op_sel_hi:[0,1]
	ds_bpermute_b32 v22, v59, v20
	ds_bpermute_b32 v23, v59, v21
	v_pk_mul_f32 v[62:63], v[230:231], v[62:63]
	ds_bpermute_b32 v64, v59, v62
	ds_bpermute_b32 v65, v59, v63
	ds_bpermute_b32 v18, v59, v76
	ds_bpermute_b32 v19, v59, v77
	s_waitcnt lgkmcnt(4)
	v_pk_mul_f32 v[22:23], v[48:49], v[22:23]
	v_pk_mul_f32 v[66:67], v[2:3], v[76:77]
	v_pk_fma_f32 v[20:21], v[4:5], v[20:21], v[22:23]
	s_waitcnt lgkmcnt(2)
	v_pk_mul_f32 v[22:23], v[52:53], v[64:65]
	s_waitcnt lgkmcnt(0)
	v_pk_fma_f32 v[18:19], v[50:51], v[18:19], v[66:67]
	v_pk_fma_f32 v[22:23], v[6:7], v[62:63], v[22:23]
	v_cvt_pk_bf16_f32 v16, v16, v17
	v_cvt_pk_bf16_f32 v17, v18, v19
	v_cvt_pk_bf16_f32 v18, v20, v21
	v_cvt_pk_bf16_f32 v19, v22, v23
	global_store_dwordx4 v[44:45], v[16:19], off offset:128
	v_lshl_add_u64 v[44:45], v[44:45], 0, s[56:57]
	s_waitcnt vmcnt(20)
	v_mov_b64_e32 v[16:17], v[180:181]
	v_mov_b64_e32 v[18:19], v[182:183]
	v_mov_b64_e32 v[20:21], v[184:185]
	v_mov_b64_e32 v[22:23], v[186:187]
	v_lshlrev_b32_e32 v94, 16, v16
	v_and_b32_e32 v95, 0xffff0000, v16
	v_lshlrev_b32_e32 v86, 16, v23
	v_and_b32_e32 v87, 0xffff0000, v23
	v_lshlrev_b32_e32 v88, 16, v22
	v_and_b32_e32 v89, 0xffff0000, v22
	v_lshlrev_b32_e32 v22, 16, v21
	v_and_b32_e32 v23, 0xffff0000, v21
	v_lshlrev_b32_e32 v90, 16, v20
	v_and_b32_e32 v91, 0xffff0000, v20
	v_lshlrev_b32_e32 v20, 16, v19
	v_and_b32_e32 v21, 0xffff0000, v19
	v_lshlrev_b32_e32 v92, 16, v18
	v_and_b32_e32 v93, 0xffff0000, v18
	v_lshlrev_b32_e32 v18, 16, v17
	v_and_b32_e32 v19, 0xffff0000, v17
	v_pk_mul_f32 v[100:101], v[94:95], v[94:95]
	v_pk_mul_f32 v[98:99], v[18:19], v[18:19]
	v_pk_fma_f32 v[100:101], v[90:91], v[90:91], v[100:101]
	v_pk_fma_f32 v[98:99], v[22:23], v[22:23], v[98:99]
	v_add_f32_e32 v24, v100, v101
	v_pk_mul_f32 v[96:97], v[92:93], v[92:93]
	v_add_f32_e32 v24, v98, v24
	v_pk_fma_f32 v[96:97], v[88:89], v[88:89], v[96:97]
	v_add_f32_e32 v24, v99, v24
	v_pk_mul_f32 v[16:17], v[20:21], v[20:21]
	v_add_f32_e32 v24, v96, v24
	v_pk_fma_f32 v[16:17], v[86:87], v[86:87], v[16:17]
	v_add_f32_e32 v24, v97, v24
	v_add_f32_e32 v16, v16, v24
	v_add_f32_e32 v16, v17, v16
	ds_bpermute_b32 v17, v57, v16
	s_waitcnt lgkmcnt(0)
	v_add_f32_e32 v16, v16, v17
	ds_bpermute_b32 v17, v58, v16
	s_waitcnt lgkmcnt(0)
	v_add_f32_e32 v16, v16, v17
	ds_bpermute_b32 v17, v59, v16
	s_waitcnt lgkmcnt(0)
	v_add_f32_e32 v16, v16, v17
	v_mul_f32_e32 v16, v26, v16
	v_fma_f32 v16, v26, v16, v60
	v_fmamk_f32 v16, v16, 0x3baaaaab, v55
	v_mul_f32_e32 v17, 0x4b800000, v16
	v_cmp_gt_f32_e32 vcc, s16, v16
	s_nop 1
	v_cndmask_b32_e32 v16, v16, v17, vcc
	v_rsq_f32_e32 v16, v16
	s_nop 0
	v_mul_f32_e32 v17, 0x45800000, v16
	v_cndmask_b32_e32 v24, v16, v17, vcc
	v_mul_f32_e32 v16, v26, v24
	v_pk_mul_f32 v[96:97], v[24:25], v[30:31] op_sel_hi:[0,1]
	v_pk_mul_f32 v[90:91], v[16:17], v[90:91] op_sel_hi:[0,1]
	v_pk_mul_f32 v[88:89], v[16:17], v[88:89] op_sel_hi:[0,1]
	v_pk_mul_f32 v[94:95], v[16:17], v[94:95] op_sel_hi:[0,1]
	v_pk_mul_f32 v[92:93], v[16:17], v[92:93] op_sel_hi:[0,1]
	v_pk_mul_f32 v[22:23], v[16:17], v[22:23] op_sel_hi:[0,1]
	v_pk_mul_f32 v[86:87], v[16:17], v[86:87] op_sel_hi:[0,1]
	v_pk_mul_f32 v[18:19], v[16:17], v[18:19] op_sel_hi:[0,1]
	v_pk_mul_f32 v[16:17], v[16:17], v[20:21] op_sel_hi:[0,1]
	v_pk_mul_f32 v[98:99], v[24:25], v[32:33] op_sel_hi:[0,1]
	v_pk_mul_f32 v[20:21], v[212:213], v[90:91]
	v_pk_mul_f32 v[62:63], v[216:217], v[88:89]
	v_pk_mul_f32 v[66:67], v[220:221], v[94:95]
	v_pk_mul_f32 v[70:71], v[224:225], v[92:93]
	v_pk_mul_f32 v[22:23], v[214:215], v[22:23]
	v_pk_mul_f32 v[74:75], v[232:233], v[96:97]
	v_pk_mul_f32 v[64:65], v[218:219], v[86:87]
	v_pk_mul_f32 v[68:69], v[222:223], v[18:19]
	v_cvt_pk_bf16_f32 v18, v62, v63
	ds_bpermute_b32 v62, v59, v74
	ds_bpermute_b32 v63, v59, v75
	v_pk_mul_f32 v[72:73], v[226:227], v[16:17]
	v_cvt_pk_bf16_f32 v16, v20, v21
	v_cvt_pk_bf16_f32 v17, v22, v23
	v_cvt_pk_bf16_f32 v19, v64, v65
	v_cvt_pk_bf16_f32 v20, v66, v67
	v_cvt_pk_bf16_f32 v21, v68, v69
	v_cvt_pk_bf16_f32 v22, v70, v71
	v_cvt_pk_bf16_f32 v23, v72, v73
	v_pk_mul_f32 v[64:65], v[0:1], v[74:75]
	global_store_dwordx4 v[44:45], v[16:19], off offset:-128
	global_store_dwordx4 v[44:45], v[20:23], off
	v_pk_mul_f32 v[76:77], v[234:235], v[98:99]
	s_waitcnt lgkmcnt(0)
	v_pk_fma_f32 v[16:17], v[46:47], v[62:63], v[64:65]
	v_pk_mul_f32 v[20:21], v[24:25], v[34:35] op_sel_hi:[0,1]
	v_pk_mul_f32 v[20:21], v[228:229], v[20:21]
	v_pk_mul_f32 v[62:63], v[24:25], v[36:37] op_sel_hi:[0,1]
	ds_bpermute_b32 v22, v59, v20
	ds_bpermute_b32 v23, v59, v21
	v_pk_mul_f32 v[62:63], v[230:231], v[62:63]
	ds_bpermute_b32 v64, v59, v62
	ds_bpermute_b32 v65, v59, v63
	ds_bpermute_b32 v18, v59, v76
	ds_bpermute_b32 v19, v59, v77
	s_waitcnt lgkmcnt(4)
	v_pk_mul_f32 v[22:23], v[48:49], v[22:23]
	v_pk_mul_f32 v[66:67], v[2:3], v[76:77]
	v_pk_fma_f32 v[20:21], v[4:5], v[20:21], v[22:23]
	s_waitcnt lgkmcnt(2)
	v_pk_mul_f32 v[22:23], v[52:53], v[64:65]
	s_waitcnt lgkmcnt(0)
	v_pk_fma_f32 v[18:19], v[50:51], v[18:19], v[66:67]
	v_pk_fma_f32 v[22:23], v[6:7], v[62:63], v[22:23]
	v_cvt_pk_bf16_f32 v16, v16, v17
	v_cvt_pk_bf16_f32 v17, v18, v19
	v_cvt_pk_bf16_f32 v18, v20, v21
	v_cvt_pk_bf16_f32 v19, v22, v23
	global_store_dwordx4 v[44:45], v[16:19], off offset:128
	v_lshl_add_u64 v[44:45], v[44:45], 0, s[56:57]
	s_waitcnt vmcnt(21)
	v_mov_b64_e32 v[16:17], v[188:189]
	v_mov_b64_e32 v[18:19], v[190:191]
	v_mov_b64_e32 v[20:21], v[192:193]
	v_mov_b64_e32 v[22:23], v[194:195]
	v_lshlrev_b32_e32 v94, 16, v16
	v_and_b32_e32 v95, 0xffff0000, v16
	v_lshlrev_b32_e32 v86, 16, v23
	v_and_b32_e32 v87, 0xffff0000, v23
	v_lshlrev_b32_e32 v88, 16, v22
	v_and_b32_e32 v89, 0xffff0000, v22
	v_lshlrev_b32_e32 v22, 16, v21
	v_and_b32_e32 v23, 0xffff0000, v21
	v_lshlrev_b32_e32 v90, 16, v20
	v_and_b32_e32 v91, 0xffff0000, v20
	v_lshlrev_b32_e32 v20, 16, v19
	v_and_b32_e32 v21, 0xffff0000, v19
	v_lshlrev_b32_e32 v92, 16, v18
	v_and_b32_e32 v93, 0xffff0000, v18
	v_lshlrev_b32_e32 v18, 16, v17
	v_and_b32_e32 v19, 0xffff0000, v17
	v_pk_mul_f32 v[100:101], v[94:95], v[94:95]
	v_pk_mul_f32 v[98:99], v[18:19], v[18:19]
	v_pk_fma_f32 v[100:101], v[90:91], v[90:91], v[100:101]
	v_pk_fma_f32 v[98:99], v[22:23], v[22:23], v[98:99]
	v_add_f32_e32 v24, v100, v101
	v_pk_mul_f32 v[96:97], v[92:93], v[92:93]
	v_add_f32_e32 v24, v98, v24
	v_pk_fma_f32 v[96:97], v[88:89], v[88:89], v[96:97]
	v_add_f32_e32 v24, v99, v24
	v_pk_mul_f32 v[16:17], v[20:21], v[20:21]
	v_add_f32_e32 v24, v96, v24
	v_pk_fma_f32 v[16:17], v[86:87], v[86:87], v[16:17]
	v_add_f32_e32 v24, v97, v24
	v_add_f32_e32 v16, v16, v24
	v_add_f32_e32 v16, v17, v16
	ds_bpermute_b32 v17, v57, v16
	s_waitcnt lgkmcnt(0)
	v_add_f32_e32 v16, v16, v17
	ds_bpermute_b32 v17, v58, v16
	s_waitcnt lgkmcnt(0)
	v_add_f32_e32 v16, v16, v17
	ds_bpermute_b32 v17, v59, v16
	s_waitcnt lgkmcnt(0)
	v_add_f32_e32 v16, v16, v17
	v_mul_f32_e32 v16, v26, v16
	v_fma_f32 v16, v26, v16, v60
	v_fmamk_f32 v16, v16, 0x3baaaaab, v55
	v_mul_f32_e32 v17, 0x4b800000, v16
	v_cmp_gt_f32_e32 vcc, s16, v16
	s_nop 1
	v_cndmask_b32_e32 v16, v16, v17, vcc
	v_rsq_f32_e32 v16, v16
	s_nop 0
	v_mul_f32_e32 v17, 0x45800000, v16
	v_cndmask_b32_e32 v24, v16, v17, vcc
	v_mul_f32_e32 v16, v26, v24
	v_pk_mul_f32 v[96:97], v[24:25], v[30:31] op_sel_hi:[0,1]
	v_pk_mul_f32 v[90:91], v[16:17], v[90:91] op_sel_hi:[0,1]
	v_pk_mul_f32 v[88:89], v[16:17], v[88:89] op_sel_hi:[0,1]
	v_pk_mul_f32 v[94:95], v[16:17], v[94:95] op_sel_hi:[0,1]
	v_pk_mul_f32 v[92:93], v[16:17], v[92:93] op_sel_hi:[0,1]
	v_pk_mul_f32 v[22:23], v[16:17], v[22:23] op_sel_hi:[0,1]
	v_pk_mul_f32 v[86:87], v[16:17], v[86:87] op_sel_hi:[0,1]
	v_pk_mul_f32 v[18:19], v[16:17], v[18:19] op_sel_hi:[0,1]
	v_pk_mul_f32 v[16:17], v[16:17], v[20:21] op_sel_hi:[0,1]
	v_pk_mul_f32 v[98:99], v[24:25], v[32:33] op_sel_hi:[0,1]
	v_pk_mul_f32 v[20:21], v[212:213], v[90:91]
	v_pk_mul_f32 v[62:63], v[216:217], v[88:89]
	v_pk_mul_f32 v[66:67], v[220:221], v[94:95]
	v_pk_mul_f32 v[70:71], v[224:225], v[92:93]
	v_pk_mul_f32 v[22:23], v[214:215], v[22:23]
	v_pk_mul_f32 v[74:75], v[232:233], v[96:97]
	v_pk_mul_f32 v[64:65], v[218:219], v[86:87]
	v_pk_mul_f32 v[68:69], v[222:223], v[18:19]
	v_cvt_pk_bf16_f32 v18, v62, v63
	ds_bpermute_b32 v62, v59, v74
	ds_bpermute_b32 v63, v59, v75
	v_pk_mul_f32 v[72:73], v[226:227], v[16:17]
	v_cvt_pk_bf16_f32 v16, v20, v21
	v_cvt_pk_bf16_f32 v17, v22, v23
	v_cvt_pk_bf16_f32 v19, v64, v65
	v_cvt_pk_bf16_f32 v20, v66, v67
	v_cvt_pk_bf16_f32 v21, v68, v69
	v_cvt_pk_bf16_f32 v22, v70, v71
	v_cvt_pk_bf16_f32 v23, v72, v73
	v_pk_mul_f32 v[64:65], v[0:1], v[74:75]
	global_store_dwordx4 v[44:45], v[16:19], off offset:-128
	global_store_dwordx4 v[44:45], v[20:23], off
	v_pk_mul_f32 v[76:77], v[234:235], v[98:99]
	s_waitcnt lgkmcnt(0)
	v_pk_fma_f32 v[16:17], v[46:47], v[62:63], v[64:65]
	v_pk_mul_f32 v[20:21], v[24:25], v[34:35] op_sel_hi:[0,1]
	v_pk_mul_f32 v[20:21], v[228:229], v[20:21]
	v_pk_mul_f32 v[62:63], v[24:25], v[36:37] op_sel_hi:[0,1]
	ds_bpermute_b32 v22, v59, v20
	ds_bpermute_b32 v23, v59, v21
	v_pk_mul_f32 v[62:63], v[230:231], v[62:63]
	ds_bpermute_b32 v64, v59, v62
	ds_bpermute_b32 v65, v59, v63
	ds_bpermute_b32 v18, v59, v76
	ds_bpermute_b32 v19, v59, v77
	s_waitcnt lgkmcnt(4)
	v_pk_mul_f32 v[22:23], v[48:49], v[22:23]
	v_pk_mul_f32 v[66:67], v[2:3], v[76:77]
	v_pk_fma_f32 v[20:21], v[4:5], v[20:21], v[22:23]
	s_waitcnt lgkmcnt(2)
	v_pk_mul_f32 v[22:23], v[52:53], v[64:65]
	s_waitcnt lgkmcnt(0)
	v_pk_fma_f32 v[18:19], v[50:51], v[18:19], v[66:67]
	v_pk_fma_f32 v[22:23], v[6:7], v[62:63], v[22:23]
	v_cvt_pk_bf16_f32 v16, v16, v17
	v_cvt_pk_bf16_f32 v17, v18, v19
	v_cvt_pk_bf16_f32 v18, v20, v21
	v_cvt_pk_bf16_f32 v19, v22, v23
	global_store_dwordx4 v[44:45], v[16:19], off offset:128
	v_lshl_add_u64 v[44:45], v[44:45], 0, s[56:57]
